# conv2d: third task round split into 8-column quarter tasks so every wave does 88 column steps (was 96 or 64)
# speedup vs baseline: 1.0137x; 1.0137x over previous
.LBB0_928:
	s_cmp_lt_i32 s76, 12
	s_cselect_b64 s[16:17], -1, 0
	s_and_b64 s[4:5], s[16:17], s[46:47]
	s_andn2_b64 vcc, exec, s[4:5]
	s_cbranch_vccnz .LBB0_979
	s_and_b32 s4, s2, 7
	s_mulk_i32 s4, 0x2c0
	s_and_b32 s5, s2, -8
	s_and_b32 s3, s38, 7
	s_lshl_b32 s10, s2, 3
	s_add_i32 s11, s4, s5
	s_add_i32 s12, s4, 0x2c0
	s_cmp_eq_u32 s3, 0
	s_cselect_b64 s[6:7], -1, 0
	s_and_b64 s[4:5], s[6:7], exec
	s_cselect_b32 s3, s11, s10
	s_waitcnt vmcnt(0)
	v_add_u32_e32 v166, s3, v197
	s_cselect_b32 s27, s12, 0x1600
	s_mov_b64 s[8:9], s[0:1]
	s_movk_i32 s3, 0x1600
	v_readfirstlane_b32 s92, v197
	s_and_b32 s93, s2, 7
	s_mulk_i32 s93, 0x2c0
	s_and_b32 s99, s2, -8
	s_add_u32 s92, s92, s99
	s_mov_b32 s98, 0
	v_cmp_gt_i32_e32 vcc, s27, v166
	s_and_saveexec_b64 s[18:19], vcc
	s_cbranch_execz .LBB0_978
	s_load_dwordx4 s[12:15], s[8:9], 0xb8
	s_load_dwordx2 s[20:21], s[8:9], 0xe0
	s_and_b32 s10, s38, -8
	s_lshl_b32 s11, s38, 3
	s_and_b64 s[4:5], s[6:7], exec
	s_cselect_b32 s29, s10, s11
	s_waitcnt lgkmcnt(0)
	s_add_u32 s22, s20, 0xd200e00
	v_lshlrev_b32_e32 v0, 2, v196
	s_addc_u32 s23, s21, 0
	v_and_b32_e32 v167, 0xfc, v0
	s_mov_b64 s[24:25], 0
	s_mov_b32 s39, 0x2e8ba2e9
	s_movk_i32 s48, 0x2000
	s_movk_i32 s49, 0x5000
	s_mov_b32 s50, 0x8000
	s_mov_b32 s51, 0xb000
	s_mov_b32 s52, 0xd000
	s_mov_b32 s53, 0x10000
	s_mov_b32 s54, 0x13000
	s_mov_b32 s55, 0x16000
	s_movk_i32 s56, 0x7c
	s_mov_b32 s57, 0x2c00000
	v_mov_b64_e32 v[40:41], s[22:23]
	s_movk_i32 s58, 0x80
	v_mov_b32_e32 v42, 0
	s_movk_i32 s59, 0x100
	s_mov_b32 s60, 0x160000
	s_mov_b32 s61, 0x23200000
	s_mov_b32 s26, 0x3dd2d3e7
	s_mov_b32 s28, 0xc0135761
	s_mov_b32 s62, 0x23202000
	s_mov_b32 s63, 0x23203000
	s_mov_b32 s88, s61
	s_mov_b32 s89, 0
	s_mov_b32 s90, s63
	s_mov_b32 s91, 0
	s_branch .LBB0_932
.LBB0_931:
	s_or_b64 exec, exec, s[30:31]
	s_add_u32 s98, s98, 1
	s_cmp_lt_u32 s98, 5
	s_cbranch_scc0 .LBB0_978
.LBB0_932:
	s_cmp_lt_u32 s98, 2
	s_cbranch_scc0 .Lq_quarter
	s_lshl_b32 s99, s98, 8
	s_add_u32 s99, s99, s92
	s_add_u32 s99, s99, s93
	s_mov_b32 s100, 0
	s_mov_b32 s101, 32
	s_branch .Lq_set
.Lq_quarter:
	s_mul_i32 s99, s92, 3
	s_add_u32 s99, s99, s98
	s_sub_u32 s99, s99, 2
	s_and_b32 s100, s99, 3
	s_lshl_b32 s100, s100, 3
	s_lshr_b32 s99, s99, 2
	s_add_u32 s99, s99, 0x200
	s_add_u32 s99, s99, s93
	s_mov_b32 s101, 8
.Lq_set:
	s_mul_i32 s94, s100, 0x1600
	v_mov_b32_e32 v166, s99
	v_mul_hi_i32 v0, v166, s39
	v_lshrrev_b32_e32 v1, 31, v0
	v_ashrrev_i32_e32 v0, 1, v0
	v_add_u32_e32 v104, v0, v1
	v_mul_lo_u32 v0, v104, 11
	v_sub_u32_e32 v0, v166, v0
	v_lshl_or_b32 v46, v0, 8, v167
	v_ashrrev_i32_e32 v47, 31, v46
	v_lshlrev_b64 v[36:37], 2, v[46:47]
	v_lshl_add_u64 v[32:33], s[12:13], 0, v[36:37]
	v_add_co_u32_e32 v4, vcc, s48, v32
	v_lshl_add_u64 v[36:37], s[14:15], 0, v[36:37]
	s_nop 0
	v_addc_co_u32_e32 v5, vcc, 0, v33, vcc
	v_add_co_u32_e32 v8, vcc, s49, v32
	flat_load_dwordx4 v[0:3], v[32:33]
	s_nop 0
	flat_load_dwordx4 v[4:7], v[4:5] offset:3072
	v_addc_co_u32_e32 v9, vcc, 0, v33, vcc
	v_add_co_u32_e32 v12, vcc, s50, v32
	v_lshlrev_b32_e32 v43, 1, v104
	s_nop 0
	v_addc_co_u32_e32 v13, vcc, 0, v33, vcc
	v_add_co_u32_e32 v16, vcc, s51, v32
	flat_load_dwordx4 v[8:11], v[8:9] offset:2048
	s_nop 0
	flat_load_dwordx4 v[12:15], v[12:13] offset:1024
	v_addc_co_u32_e32 v17, vcc, 0, v33, vcc
	v_add_co_u32_e32 v20, vcc, s52, v32
	v_lshlrev_b32_e32 v44, 5, v104
	s_nop 0
	v_addc_co_u32_e32 v21, vcc, 0, v33, vcc
	v_add_co_u32_e32 v24, vcc, s53, v32
	flat_load_dwordx4 v[16:19], v[16:17]
	s_nop 0
	flat_load_dwordx4 v[20:23], v[20:21] offset:3072
	v_addc_co_u32_e32 v25, vcc, 0, v33, vcc
	v_add_co_u32_e32 v28, vcc, s54, v32
	v_and_b32_e32 v60, 0x7c, v43
	s_nop 0
	v_addc_co_u32_e32 v29, vcc, 0, v33, vcc
	v_add_co_u32_e32 v32, vcc, s55, v32
	flat_load_dwordx4 v[24:27], v[24:25] offset:2048
	s_nop 0
	flat_load_dwordx4 v[28:31], v[28:29] offset:1024
	v_addc_co_u32_e32 v33, vcc, 0, v33, vcc
	flat_load_dwordx4 v[32:35], v[32:33]
	v_and_b32_e32 v168, 32, v44
	v_add_u32_e32 v168, s100, v168
	flat_load_dwordx4 v[36:39], v[36:37]
	v_ashrrev_i32_e32 v105, 6, v104
	v_add_u32_e32 v43, -1, v168
	v_add_u32_e32 v62, -1, v60
	v_mad_i64_i32 v[44:45], s[4:5], v105, s57, v[40:41]
	v_cmp_gt_u32_e64 s[10:11], 64, v43
	v_cmp_gt_u32_e64 s[6:7], s58, v62
	v_lshl_add_u64 v[44:45], v[46:47], 1, v[44:45]
	s_and_b64 s[4:5], s[10:11], s[6:7]
	v_mov_b32_e32 v48, v42
	v_mov_b32_e32 v49, v42
	s_and_saveexec_b64 s[8:9], s[4:5]
	s_cbranch_execz .LBB0_934
	v_lshl_or_b32 v48, v62, 6, v43
	v_mul_i32_i24_e32 v48, 0x1600, v48
	v_mov_b32_e32 v49, v42
	v_lshl_add_u64 v[48:49], v[44:45], 0, v[48:49]
	flat_load_dwordx2 v[48:49], v[48:49]

.LBB0_948:
	s_or_b64 exec, exec, s[10:11]
	s_waitcnt vmcnt(0) lgkmcnt(0)
	v_lshlrev_b32_e32 v82, 16, v54
	v_and_b32_e32 v83, 0xffff0000, v54
	v_lshlrev_b64 v[46:47], 1, v[46:47]
	v_and_b32_e32 v54, 1, v104
	v_lshlrev_b32_e32 v78, 16, v52
	v_and_b32_e32 v79, 0xffff0000, v52
	v_lshlrev_b32_e32 v112, 16, v60
	v_and_b32_e32 v113, 0xffff0000, v60
	v_lshlrev_b32_e32 v114, 16, v61
	v_and_b32_e32 v115, 0xffff0000, v61
	v_mad_i64_i32 v[60:61], s[4:5], v105, s57, v[46:47]
	v_add_u32_e32 v43, v110, v168
	v_bfe_u32 v52, v104, 1, 5
	v_mul_u32_u24_e32 v54, 0x2c000, v54
	v_lshlrev_b32_e32 v72, 16, v48
	v_and_b32_e32 v73, 0xffff0000, v48
	v_lshlrev_b32_e32 v76, 16, v49
	v_and_b32_e32 v77, 0xffff0000, v49
	v_lshlrev_b32_e32 v106, 16, v100
	v_and_b32_e32 v107, 0xffff0000, v100
	v_add_u32_e32 v46, 0x80, v43
	v_mad_u64_u32 v[48:49], s[4:5], v43, s3, v[60:61]
	v_add_u32_e32 v100, v111, v168
	v_mad_u32_u24 v52, v52, s60, v54
	v_add_u32_e32 v52, s94, v52
	v_add_u32_e32 v54, 64, v43
	v_add_u32_e32 v43, 0xc0, v43
	v_lshlrev_b32_e32 v98, 16, v56
	v_and_b32_e32 v99, 0xffff0000, v56
	v_mul_u32_u24_e32 v56, 0x1600, v43
	v_add_u32_e32 v43, 4, v100
	v_lshlrev_b32_e32 v90, 16, v50
	v_and_b32_e32 v91, 0xffff0000, v50
	v_lshlrev_b32_e32 v62, 16, v58
	v_and_b32_e32 v63, 0xffff0000, v58
	v_add_u32_e32 v50, 3, v100
	v_mul_u32_u24_e32 v58, 0x1600, v43
	v_add_u32_e32 v43, 2, v100
	v_lshlrev_b32_e32 v84, 16, v55
	v_and_b32_e32 v85, 0xffff0000, v55
	v_lshlrev_b32_e32 v92, 16, v51
	v_and_b32_e32 v93, 0xffff0000, v51
	v_lshlrev_b32_e32 v102, 16, v57
	v_and_b32_e32 v103, 0xffff0000, v57
	v_lshlrev_b32_e32 v64, 16, v59
	v_and_b32_e32 v65, 0xffff0000, v59
	v_lshlrev_b32_e32 v108, 16, v101
	v_and_b32_e32 v109, 0xffff0000, v101
	v_mul_u32_u24_e32 v46, 0x1600, v46
	v_mov_b32_e32 v47, v42
	v_mul_u32_u24_e32 v50, 0x1600, v50
	v_mov_b32_e32 v51, v42
	v_mul_u32_u24_e32 v54, 0x1600, v54
	v_mov_b32_e32 v55, v42
	v_mov_b32_e32 v57, v42
	v_mov_b32_e32 v59, v42
	v_mul_u32_u24_e32 v100, 0x1600, v43
	v_mov_b32_e32 v101, v42
	v_lshl_add_u64 v[46:47], v[60:61], 0, v[46:47]
	v_lshl_add_u64 v[50:51], v[60:61], 0, v[50:51]
	v_lshl_add_u64 v[54:55], v[60:61], 0, v[54:55]
	v_lshl_add_u64 v[56:57], v[60:61], 0, v[56:57]
	v_lshl_add_u64 v[58:59], v[60:61], 0, v[58:59]
	v_lshl_add_u64 v[60:61], v[60:61], 0, v[100:101]
	v_lshlrev_b32_e32 v80, 16, v53
	v_and_b32_e32 v81, 0xffff0000, v53
	v_lshlrev_b32_e32 v66, 16, v68
	v_and_b32_e32 v67, 0xffff0000, v68
	v_lshlrev_b32_e32 v68, 16, v69
	v_and_b32_e32 v69, 0xffff0000, v69
	v_lshlrev_b32_e32 v70, 16, v74
	v_and_b32_e32 v71, 0xffff0000, v74
	v_lshlrev_b32_e32 v74, 16, v75
	v_and_b32_e32 v75, 0xffff0000, v75
	v_lshlrev_b32_e32 v86, 16, v88
	v_and_b32_e32 v87, 0xffff0000, v88
	v_lshlrev_b32_e32 v88, 16, v89
	v_and_b32_e32 v89, 0xffff0000, v89
	v_lshlrev_b32_e32 v94, 16, v96
	v_and_b32_e32 v95, 0xffff0000, v96
	v_lshlrev_b32_e32 v96, 16, v97
	v_and_b32_e32 v97, 0xffff0000, v97
	v_add_u32_e32 v53, s101, v168
	v_lshl_add_u64 v[46:47], s[20:21], 0, v[46:47]
	v_lshl_add_u64 v[48:49], s[20:21], 0, v[48:49]
	v_lshl_add_u64 v[50:51], s[22:23], 0, v[50:51]
	v_lshl_add_u64 v[54:55], s[20:21], 0, v[54:55]
	v_lshl_add_u64 v[56:57], s[20:21], 0, v[56:57]
	v_lshl_add_u64 v[58:59], s[22:23], 0, v[58:59]
	v_lshl_add_u64 v[60:61], s[22:23], 0, v[60:61]
	s_mov_b64 s[30:31], 0
	s_mov_b64 s[34:35], 0
	s_branch .LBB0_951
.LBB0_949:
	s_or_b64 exec, exec, s[10:11]
	v_add_co_u32_e32 v86, vcc, s63, v128
	v_pk_mul_f32 v[94:95], v[6:7], v[76:77]
	s_nop 0
	v_addc_co_u32_e32 v87, vcc, 0, v129, vcc
	flat_load_dwordx2 v[88:89], v[86:87] offset:2560
	v_lshl_add_u64 v[178:179], v[116:117], 0, s[90:91]
	v_lshl_add_u64 v[180:181], v[110:111], 0, s[90:91]
	v_lshl_add_u64 v[182:183], v[100:101], 0, s[90:91]
	global_load_dwordx2 v[184:185], v[178:179], off offset:2560
	global_load_dwordx2 v[186:187], v[180:181], off offset:2560
	global_load_dwordx2 v[188:189], v[182:183], off offset:2560
	v_pk_mul_f32 v[96:97], v[4:5], v[72:73]
	v_lshlrev_b32_e32 v62, 16, v148
	v_and_b32_e32 v63, 0xffff0000, v148
	v_lshlrev_b32_e32 v64, 16, v149
	v_and_b32_e32 v65, 0xffff0000, v149
	v_pk_mul_f32 v[106:107], v[18:19], v[80:81]
	v_pk_mul_f32 v[108:109], v[16:17], v[78:79]
	v_pk_fma_f32 v[94:95], v[2:3], v[144:145], v[94:95]
	v_pk_fma_f32 v[96:97], v[0:1], v[142:143], v[96:97]
	v_lshlrev_b32_e32 v66, 16, v152
	v_and_b32_e32 v67, 0xffff0000, v152
	v_lshlrev_b32_e32 v68, 16, v153
	v_and_b32_e32 v69, 0xffff0000, v153
	v_lshlrev_b32_e32 v70, 16, v150
	v_and_b32_e32 v71, 0xffff0000, v150
	v_lshlrev_b32_e32 v74, 16, v151
	v_and_b32_e32 v75, 0xffff0000, v151
	v_pk_mul_f32 v[148:149], v[30:31], v[84:85]
	v_pk_mul_f32 v[150:151], v[28:29], v[82:83]
	v_pk_fma_f32 v[106:107], v[14:15], v[136:137], v[106:107]
	v_pk_fma_f32 v[108:109], v[12:13], v[134:135], v[108:109]
	v_pk_fma_f32 v[94:95], v[10:11], v[64:65], v[94:95]
	v_pk_fma_f32 v[96:97], v[8:9], v[62:63], v[96:97]
	v_pk_fma_f32 v[142:143], v[26:27], v[126:127], v[148:149]
	v_pk_fma_f32 v[144:145], v[24:25], v[122:123], v[150:151]
	v_pk_fma_f32 v[106:107], v[22:23], v[68:69], v[106:107]
	v_pk_fma_f32 v[108:109], v[20:21], v[66:67], v[108:109]
	v_pk_add_f32 v[94:95], v[38:39], v[94:95]
	v_pk_add_f32 v[96:97], v[36:37], v[96:97]
	v_pk_fma_f32 v[142:143], v[34:35], v[74:75], v[142:143]
	v_pk_fma_f32 v[144:145], v[32:33], v[70:71], v[144:145]
	v_pk_add_f32 v[94:95], v[106:107], v[94:95]
	v_pk_add_f32 v[96:97], v[108:109], v[96:97]
	v_pk_add_f32 v[94:95], v[142:143], v[94:95]
	v_pk_add_f32 v[96:97], v[144:145], v[96:97]
	v_mov_b64_e32 v[128:129], s[28:29]
	v_pk_mul_f32 v[106:107], v[94:95], v[94:95]
	v_pk_mul_f32 v[108:109], v[96:97], v[96:97]
	v_pk_fma_f32 v[106:107], v[106:107], s[26:27], v[128:129] op_sel_hi:[1,0,0] neg_lo:[1,0,0] neg_hi:[1,0,0]
	v_pk_fma_f32 v[108:109], v[108:109], s[26:27], v[128:129] op_sel_hi:[1,0,0] neg_lo:[1,0,0] neg_hi:[1,0,0]
	v_pk_mul_f32 v[106:107], v[94:95], v[106:107]
	v_pk_mul_f32 v[108:109], v[96:97], v[108:109]
	v_exp_f32_e32 v106, v106
	v_exp_f32_e32 v108, v108
	v_exp_f32_e32 v109, v109
	v_exp_f32_e32 v107, v107
	v_add_co_u32_e32 v116, vcc, s63, v116
	v_pk_add_f32 v[108:109], v[108:109], 1.0 op_sel_hi:[1,0]
	v_pk_add_f32 v[106:107], v[106:107], 1.0 op_sel_hi:[1,0]
	v_rcp_f32_e32 v108, v108
	v_rcp_f32_e32 v109, v109
	v_rcp_f32_e32 v106, v106
	v_rcp_f32_e32 v107, v107
	v_addc_co_u32_e32 v117, vcc, 0, v117, vcc
	v_pk_mul_f32 v[96:97], v[96:97], v[108:109]
	v_pk_mul_f32 v[94:95], v[94:95], v[106:107]
	v_pk_mul_f32 v[108:109], v[18:19], v[84:85]
	v_pk_mul_f32 v[142:143], v[16:17], v[82:83]
	v_pk_mul_f32 v[144:145], v[30:31], v[92:93]
	v_pk_fma_f32 v[108:109], v[14:15], v[126:127], v[108:109]
	v_add_co_u32_e32 v110, vcc, s63, v110
	v_pk_fma_f32 v[108:109], v[22:23], v[74:75], v[108:109]
	s_nop 0
	v_addc_co_u32_e32 v111, vcc, 0, v111, vcc
	v_add_co_u32_e32 v100, vcc, s63, v100
	s_waitcnt vmcnt(0) lgkmcnt(0)
	v_mov_b64_e32 v[148:149], v[158:159]
	v_addc_co_u32_e32 v101, vcc, 0, v101, vcc
	v_mov_b64_e32 v[152:153], v[154:155]
	v_mov_b64_e32 v[150:151], v[156:157]
	v_lshlrev_b32_e32 v43, 16, v88
	v_and_b32_e32 v88, 0xffff0000, v88
	v_lshlrev_b32_e32 v106, 16, v89
	v_and_b32_e32 v89, 0xffff0000, v89
	v_mul_f32_e32 v88, v97, v88
	v_mul_f32_e32 v89, v95, v89
	v_mul_f32_e32 v43, v96, v43
	v_mul_f32_e32 v94, v94, v106
	v_cvt_pk_bf16_f32 v88, v43, v88
	v_cvt_pk_bf16_f32 v89, v94, v89
	flat_store_dwordx2 v[86:87], v[88:89] offset:2560
	s_nop 1
	v_mov_b64_e32 v[94:95], v[184:185]
	v_pk_mul_f32 v[96:97], v[6:7], v[80:81]
	v_pk_mul_f32 v[106:107], v[4:5], v[78:79]
	v_pk_fma_f32 v[96:97], v[2:3], v[136:137], v[96:97]
	v_pk_fma_f32 v[106:107], v[0:1], v[134:135], v[106:107]
	v_lshlrev_b32_e32 v86, 16, v146
	v_and_b32_e32 v87, 0xffff0000, v146
	v_lshlrev_b32_e32 v88, 16, v147
	v_and_b32_e32 v89, 0xffff0000, v147
	v_pk_mul_f32 v[146:147], v[28:29], v[90:91]
	v_pk_fma_f32 v[134:135], v[12:13], v[122:123], v[142:143]
	v_pk_fma_f32 v[96:97], v[10:11], v[68:69], v[96:97]
	v_pk_fma_f32 v[106:107], v[8:9], v[66:67], v[106:107]
	v_pk_fma_f32 v[136:137], v[26:27], v[120:121], v[144:145]
	v_pk_fma_f32 v[142:143], v[24:25], v[118:119], v[146:147]
	v_pk_fma_f32 v[134:135], v[20:21], v[70:71], v[134:135]
	v_pk_add_f32 v[96:97], v[38:39], v[96:97]
	v_pk_add_f32 v[106:107], v[36:37], v[106:107]
	v_pk_fma_f32 v[136:137], v[34:35], v[88:89], v[136:137]
	v_pk_fma_f32 v[142:143], v[32:33], v[86:87], v[142:143]
	v_pk_add_f32 v[96:97], v[108:109], v[96:97]
	v_pk_add_f32 v[106:107], v[134:135], v[106:107]
	v_pk_add_f32 v[96:97], v[136:137], v[96:97]
	v_pk_add_f32 v[106:107], v[142:143], v[106:107]
	v_pk_mul_f32 v[108:109], v[96:97], v[96:97]
	v_pk_mul_f32 v[134:135], v[106:107], v[106:107]
	v_pk_fma_f32 v[108:109], v[108:109], s[26:27], v[128:129] op_sel_hi:[1,0,0] neg_lo:[1,0,0] neg_hi:[1,0,0]
	v_pk_fma_f32 v[134:135], v[134:135], s[26:27], v[128:129] op_sel_hi:[1,0,0] neg_lo:[1,0,0] neg_hi:[1,0,0]
	v_pk_mul_f32 v[108:109], v[96:97], v[108:109]
	v_pk_mul_f32 v[134:135], v[106:107], v[134:135]
	v_exp_f32_e32 v108, v108
	v_exp_f32_e32 v134, v134
	v_exp_f32_e32 v135, v135
	v_exp_f32_e32 v109, v109
	v_pk_mul_f32 v[136:137], v[30:31], v[102:103]
	v_pk_mul_f32 v[142:143], v[28:29], v[98:99]
	v_pk_add_f32 v[134:135], v[134:135], 1.0 op_sel_hi:[1,0]
	v_pk_add_f32 v[108:109], v[108:109], 1.0 op_sel_hi:[1,0]
	v_rcp_f32_e32 v134, v134
	v_rcp_f32_e32 v135, v135
	v_rcp_f32_e32 v108, v108
	v_rcp_f32_e32 v109, v109
	v_mov_b64_e32 v[146:147], v[160:161]
	v_pk_mul_f32 v[106:107], v[106:107], v[134:135]
	v_pk_mul_f32 v[134:135], v[16:17], v[90:91]
	v_pk_mul_f32 v[96:97], v[96:97], v[108:109]
	s_nop 0
	v_lshlrev_b32_e32 v43, 16, v94
	v_and_b32_e32 v94, 0xffff0000, v94
	v_lshlrev_b32_e32 v108, 16, v95
	v_and_b32_e32 v95, 0xffff0000, v95
	v_mul_f32_e32 v94, v107, v94
	v_mul_f32_e32 v95, v97, v95
	v_mul_f32_e32 v43, v106, v43
	v_mul_f32_e32 v96, v96, v108
	v_cvt_pk_bf16_f32 v94, v43, v94
	v_cvt_pk_bf16_f32 v95, v96, v95
	flat_store_dwordx2 v[116:117], v[94:95] offset:2560
	s_nop 1
	v_mov_b64_e32 v[106:107], v[186:187]
	v_pk_mul_f32 v[108:109], v[6:7], v[84:85]
	v_pk_mul_f32 v[116:117], v[4:5], v[82:83]
	v_lshlrev_b32_e32 v94, 16, v124
	v_and_b32_e32 v95, 0xffff0000, v124
	v_lshlrev_b32_e32 v96, 16, v125
	v_and_b32_e32 v97, 0xffff0000, v125
	v_pk_mul_f32 v[124:125], v[18:19], v[92:93]
	v_pk_fma_f32 v[108:109], v[2:3], v[126:127], v[108:109]
	v_pk_fma_f32 v[116:117], v[0:1], v[122:123], v[116:117]
	v_pk_fma_f32 v[122:123], v[14:15], v[120:121], v[124:125]
	v_pk_fma_f32 v[124:125], v[12:13], v[118:119], v[134:135]
	v_pk_fma_f32 v[108:109], v[10:11], v[74:75], v[108:109]
	v_pk_fma_f32 v[116:117], v[8:9], v[70:71], v[116:117]
	v_pk_fma_f32 v[126:127], v[26:27], v[132:133], v[136:137]
	v_pk_fma_f32 v[134:135], v[24:25], v[130:131], v[142:143]
	v_pk_fma_f32 v[122:123], v[22:23], v[88:89], v[122:123]
	v_pk_fma_f32 v[124:125], v[20:21], v[86:87], v[124:125]
	v_pk_add_f32 v[108:109], v[38:39], v[108:109]
	v_pk_add_f32 v[116:117], v[36:37], v[116:117]
	v_pk_fma_f32 v[126:127], v[34:35], v[96:97], v[126:127]
	v_pk_fma_f32 v[134:135], v[32:33], v[94:95], v[134:135]
	v_pk_add_f32 v[108:109], v[122:123], v[108:109]
	v_pk_add_f32 v[116:117], v[124:125], v[116:117]
	v_pk_add_f32 v[108:109], v[126:127], v[108:109]
	v_pk_add_f32 v[116:117], v[134:135], v[116:117]
	v_pk_mul_f32 v[122:123], v[108:109], v[108:109]
	v_pk_mul_f32 v[124:125], v[116:117], v[116:117]
	v_pk_fma_f32 v[122:123], v[122:123], s[26:27], v[128:129] op_sel_hi:[1,0,0] neg_lo:[1,0,0] neg_hi:[1,0,0]
	v_pk_fma_f32 v[124:125], v[124:125], s[26:27], v[128:129] op_sel_hi:[1,0,0] neg_lo:[1,0,0] neg_hi:[1,0,0]
	v_pk_mul_f32 v[122:123], v[108:109], v[122:123]
	v_pk_mul_f32 v[124:125], v[116:117], v[124:125]
	v_exp_f32_e32 v122, v122
	v_exp_f32_e32 v124, v124
	v_exp_f32_e32 v125, v125
	v_exp_f32_e32 v123, v123
	v_pk_mul_f32 v[126:127], v[30:31], v[114:115]
	v_pk_mul_f32 v[134:135], v[28:29], v[112:113]
	v_pk_add_f32 v[124:125], v[124:125], 1.0 op_sel_hi:[1,0]
	v_pk_add_f32 v[122:123], v[122:123], 1.0 op_sel_hi:[1,0]
	v_rcp_f32_e32 v124, v124
	v_rcp_f32_e32 v125, v125
	v_rcp_f32_e32 v122, v122
	v_rcp_f32_e32 v123, v123
	v_pk_mul_f32 v[116:117], v[116:117], v[124:125]
	v_pk_mul_f32 v[124:125], v[16:17], v[98:99]
	v_pk_mul_f32 v[108:109], v[108:109], v[122:123]
	s_nop 0
	v_lshlrev_b32_e32 v43, 16, v106
	v_and_b32_e32 v106, 0xffff0000, v106
	v_lshlrev_b32_e32 v122, 16, v107
	v_and_b32_e32 v107, 0xffff0000, v107
	v_mul_f32_e32 v106, v117, v106
	v_mul_f32_e32 v107, v109, v107
	v_mul_f32_e32 v43, v116, v43
	v_mul_f32_e32 v108, v108, v122
	v_cvt_pk_bf16_f32 v106, v43, v106
	v_cvt_pk_bf16_f32 v107, v108, v107
	flat_store_dwordx2 v[110:111], v[106:107] offset:2560
	s_nop 1
	v_mov_b64_e32 v[110:111], v[188:189]
	v_lshlrev_b32_e32 v106, 16, v104
	v_and_b32_e32 v107, 0xffff0000, v104
	v_lshlrev_b32_e32 v108, 16, v105
	v_and_b32_e32 v109, 0xffff0000, v105
	v_pk_mul_f32 v[104:105], v[6:7], v[92:93]
	v_pk_mul_f32 v[116:117], v[4:5], v[90:91]
	v_pk_mul_f32 v[122:123], v[18:19], v[102:103]
	v_pk_fma_f32 v[104:105], v[2:3], v[120:121], v[104:105]
	v_pk_fma_f32 v[116:117], v[0:1], v[118:119], v[116:117]
	v_pk_fma_f32 v[118:119], v[14:15], v[132:133], v[122:123]
	v_pk_fma_f32 v[104:105], v[10:11], v[88:89], v[104:105]
	v_pk_fma_f32 v[120:121], v[12:13], v[130:131], v[124:125]
	v_pk_fma_f32 v[122:123], v[26:27], v[140:141], v[126:127]
	v_pk_fma_f32 v[116:117], v[8:9], v[86:87], v[116:117]
	v_pk_fma_f32 v[118:119], v[22:23], v[96:97], v[118:119]
	v_pk_add_f32 v[104:105], v[38:39], v[104:105]
	v_pk_fma_f32 v[124:125], v[24:25], v[138:139], v[134:135]
	v_pk_fma_f32 v[120:121], v[20:21], v[94:95], v[120:121]
	v_pk_fma_f32 v[122:123], v[34:35], v[108:109], v[122:123]
	v_pk_add_f32 v[116:117], v[36:37], v[116:117]
	v_pk_add_f32 v[104:105], v[118:119], v[104:105]
	v_pk_fma_f32 v[124:125], v[32:33], v[106:107], v[124:125]
	v_pk_add_f32 v[116:117], v[120:121], v[116:117]
	v_pk_add_f32 v[104:105], v[122:123], v[104:105]
	v_pk_add_f32 v[116:117], v[124:125], v[116:117]
	v_pk_mul_f32 v[118:119], v[104:105], v[104:105]
	v_pk_mul_f32 v[120:121], v[116:117], v[116:117]
	v_pk_fma_f32 v[118:119], v[118:119], s[26:27], v[128:129] op_sel_hi:[1,0,0] neg_lo:[1,0,0] neg_hi:[1,0,0]
	v_pk_fma_f32 v[120:121], v[120:121], s[26:27], v[128:129] op_sel_hi:[1,0,0] neg_lo:[1,0,0] neg_hi:[1,0,0]
	v_pk_mul_f32 v[118:119], v[104:105], v[118:119]
	v_pk_mul_f32 v[120:121], v[116:117], v[120:121]
	v_exp_f32_e32 v118, v118
	v_exp_f32_e32 v119, v119
	v_exp_f32_e32 v120, v120
	v_exp_f32_e32 v121, v121
	v_mov_b64_e32 v[124:125], v[162:163]
	v_pk_add_f32 v[118:119], v[118:119], 1.0 op_sel_hi:[1,0]
	v_pk_add_f32 v[120:121], v[120:121], 1.0 op_sel_hi:[1,0]
	v_rcp_f32_e32 v118, v118
	v_rcp_f32_e32 v119, v119
	v_rcp_f32_e32 v120, v120
	v_rcp_f32_e32 v121, v121
	v_pk_mul_f32 v[104:105], v[104:105], v[118:119]
	v_pk_mul_f32 v[116:117], v[116:117], v[120:121]
	s_nop 0
	v_lshlrev_b32_e32 v118, 16, v111
	v_and_b32_e32 v111, 0xffff0000, v111
	v_lshlrev_b32_e32 v43, 16, v110
	v_and_b32_e32 v110, 0xffff0000, v110
	v_mul_f32_e32 v105, v105, v111
	v_mul_f32_e32 v43, v116, v43
	v_mul_f32_e32 v110, v117, v110
	v_mul_f32_e32 v116, v104, v118
	v_cvt_pk_bf16_f32 v104, v43, v110
	v_cvt_pk_bf16_f32 v105, v116, v105
	flat_store_dwordx2 v[100:101], v[104:105] offset:2560
	v_mov_b64_e32 v[104:105], v[164:165]

.LBB0_959:
	s_or_b64 exec, exec, s[10:11]
	v_add_co_u32_e32 v130, vcc, s61, v128
	v_lshlrev_b32_e32 v142, 16, v118
	s_nop 0
	v_addc_co_u32_e32 v131, vcc, 0, v129, vcc
	flat_load_dwordx2 v[138:139], v[130:131] offset:3584
	v_lshl_add_u64 v[178:179], v[116:117], 0, s[88:89]
	v_lshl_add_u64 v[180:181], v[110:111], 0, s[88:89]
	v_lshl_add_u64 v[182:183], v[100:101], 0, s[88:89]
	global_load_dwordx2 v[184:185], v[178:179], off offset:3584
	global_load_dwordx2 v[186:187], v[180:181], off offset:3584
	global_load_dwordx2 v[188:189], v[182:183], off offset:3584
	v_and_b32_e32 v143, 0xffff0000, v118
	v_lshlrev_b32_e32 v144, 16, v119
	v_and_b32_e32 v145, 0xffff0000, v119
	v_pk_mul_f32 v[118:119], v[6:7], v[64:65]
	v_pk_mul_f32 v[156:157], v[4:5], v[62:63]
	v_pk_mul_f32 v[158:159], v[18:19], v[68:69]
	v_pk_fma_f32 v[118:119], v[2:3], v[76:77], v[118:119]
	v_lshlrev_b32_e32 v136, 16, v123
	v_and_b32_e32 v137, 0xffff0000, v123
	v_pk_mul_f32 v[160:161], v[16:17], v[66:67]
	v_pk_mul_f32 v[162:163], v[30:31], v[74:75]
	v_pk_fma_f32 v[156:157], v[0:1], v[72:73], v[156:157]
	v_pk_fma_f32 v[158:159], v[14:15], v[80:81], v[158:159]
	v_pk_fma_f32 v[118:119], v[10:11], v[144:145], v[118:119]
	v_lshlrev_b32_e32 v134, 16, v122
	v_and_b32_e32 v135, 0xffff0000, v122
	v_lshlrev_b32_e32 v122, 16, v126
	v_and_b32_e32 v123, 0xffff0000, v126
	v_lshlrev_b32_e32 v126, 16, v127
	v_and_b32_e32 v127, 0xffff0000, v127
	v_pk_mul_f32 v[164:165], v[28:29], v[70:71]
	v_pk_fma_f32 v[160:161], v[12:13], v[78:79], v[160:161]
	v_pk_fma_f32 v[162:163], v[26:27], v[84:85], v[162:163]
	v_pk_fma_f32 v[156:157], v[8:9], v[142:143], v[156:157]
	v_pk_fma_f32 v[158:159], v[22:23], v[136:137], v[158:159]
	v_pk_add_f32 v[118:119], v[38:39], v[118:119]
	v_pk_fma_f32 v[164:165], v[24:25], v[82:83], v[164:165]
	v_pk_fma_f32 v[160:161], v[20:21], v[134:135], v[160:161]
	v_pk_fma_f32 v[162:163], v[34:35], v[126:127], v[162:163]
	v_pk_add_f32 v[156:157], v[36:37], v[156:157]
	v_pk_add_f32 v[118:119], v[118:119], v[158:159]
	v_pk_fma_f32 v[164:165], v[32:33], v[122:123], v[164:165]
	v_pk_add_f32 v[156:157], v[156:157], v[160:161]
	v_pk_add_f32 v[118:119], v[118:119], v[162:163]
	v_mov_b64_e32 v[154:155], s[28:29]
	v_pk_add_f32 v[156:157], v[156:157], v[164:165]
	v_pk_mul_f32 v[158:159], v[118:119], v[118:119]
	v_pk_mul_f32 v[160:161], v[156:157], v[156:157]
	v_pk_fma_f32 v[158:159], v[158:159], s[26:27], v[154:155] op_sel_hi:[1,0,0] neg_lo:[1,0,0] neg_hi:[1,0,0]
	v_pk_fma_f32 v[160:161], v[160:161], s[26:27], v[154:155] op_sel_hi:[1,0,0] neg_lo:[1,0,0] neg_hi:[1,0,0]
	v_pk_mul_f32 v[158:159], v[118:119], v[158:159]
	v_pk_mul_f32 v[160:161], v[156:157], v[160:161]
	v_exp_f32_e32 v158, v158
	v_exp_f32_e32 v159, v159
	v_exp_f32_e32 v160, v160
	v_exp_f32_e32 v161, v161
	v_add_co_u32_e32 v162, vcc, s61, v116
	v_pk_add_f32 v[158:159], v[158:159], 1.0 op_sel_hi:[1,0]
	v_pk_add_f32 v[160:161], v[160:161], 1.0 op_sel_hi:[1,0]
	v_rcp_f32_e32 v158, v158
	v_rcp_f32_e32 v159, v159
	v_rcp_f32_e32 v160, v160
	v_rcp_f32_e32 v161, v161
	v_addc_co_u32_e32 v163, vcc, 0, v117, vcc
	v_pk_mul_f32 v[118:119], v[118:119], v[158:159]
	v_pk_mul_f32 v[156:157], v[156:157], v[160:161]
	v_pk_mul_f32 v[160:161], v[16:17], v[70:71]
	v_pk_mul_f32 v[164:165], v[30:31], v[88:89]
	v_pk_mul_f32 v[170:171], v[28:29], v[86:87]
	v_pk_fma_f32 v[160:161], v[12:13], v[82:83], v[160:161]
	v_pk_fma_f32 v[170:171], v[24:25], v[90:91], v[170:171]
	v_pk_fma_f32 v[164:165], v[26:27], v[92:93], v[164:165]
	v_pk_fma_f32 v[160:161], v[20:21], v[122:123], v[160:161]
	v_pk_mul_f32 v[172:173], v[28:29], v[94:95]
	v_pk_mul_f32 v[174:175], v[28:29], v[106:107]
	v_pk_fma_f32 v[172:173], v[24:25], v[98:99], v[172:173]
	v_pk_fma_f32 v[174:175], v[24:25], v[112:113], v[174:175]
	s_waitcnt vmcnt(0) lgkmcnt(0)
	v_lshlrev_b32_e32 v158, 16, v139
	v_and_b32_e32 v139, 0xffff0000, v139
	v_lshlrev_b32_e32 v43, 16, v138
	v_and_b32_e32 v138, 0xffff0000, v138
	v_mul_f32_e32 v119, v119, v139
	v_mul_f32_e32 v43, v156, v43
	v_mul_f32_e32 v138, v157, v138
	v_mul_f32_e32 v156, v118, v158
	v_cvt_pk_bf16_f32 v118, v43, v138
	v_cvt_pk_bf16_f32 v119, v156, v119
	flat_store_dwordx2 v[130:131], v[118:119] offset:3584
	s_nop 1
	v_mov_b64_e32 v[130:131], v[184:185]
	v_pk_mul_f32 v[138:139], v[6:7], v[68:69]
	v_pk_mul_f32 v[156:157], v[4:5], v[66:67]
	v_pk_mul_f32 v[158:159], v[18:19], v[74:75]
	v_pk_fma_f32 v[156:157], v[0:1], v[78:79], v[156:157]
	v_pk_fma_f32 v[138:139], v[2:3], v[80:81], v[138:139]
	v_pk_fma_f32 v[158:159], v[14:15], v[84:85], v[158:159]
	v_pk_fma_f32 v[138:139], v[10:11], v[136:137], v[138:139]
	v_pk_fma_f32 v[156:157], v[8:9], v[134:135], v[156:157]
	v_lshlrev_b32_e32 v118, 16, v120
	v_and_b32_e32 v119, 0xffff0000, v120
	v_lshlrev_b32_e32 v120, 16, v121
	v_and_b32_e32 v121, 0xffff0000, v121
	v_pk_fma_f32 v[158:159], v[22:23], v[126:127], v[158:159]
	v_pk_add_f32 v[156:157], v[36:37], v[156:157]
	v_pk_add_f32 v[138:139], v[38:39], v[138:139]
	v_pk_fma_f32 v[164:165], v[34:35], v[120:121], v[164:165]
	v_pk_fma_f32 v[170:171], v[32:33], v[118:119], v[170:171]
	v_pk_add_f32 v[138:139], v[138:139], v[158:159]
	v_pk_add_f32 v[156:157], v[156:157], v[160:161]
	v_pk_add_f32 v[138:139], v[138:139], v[164:165]
	v_pk_add_f32 v[156:157], v[156:157], v[170:171]
	v_pk_mul_f32 v[158:159], v[138:139], v[138:139]
	v_pk_mul_f32 v[160:161], v[156:157], v[156:157]
	v_pk_fma_f32 v[158:159], v[158:159], s[26:27], v[154:155] op_sel_hi:[1,0,0] neg_lo:[1,0,0] neg_hi:[1,0,0]
	v_pk_fma_f32 v[160:161], v[160:161], s[26:27], v[154:155] op_sel_hi:[1,0,0] neg_lo:[1,0,0] neg_hi:[1,0,0]
	v_pk_mul_f32 v[158:159], v[138:139], v[158:159]
	v_pk_mul_f32 v[160:161], v[156:157], v[160:161]
	v_exp_f32_e32 v158, v158
	v_exp_f32_e32 v160, v160
	v_exp_f32_e32 v161, v161
	v_exp_f32_e32 v159, v159
	v_add_co_u32_e32 v164, vcc, s61, v110
	v_pk_add_f32 v[160:161], v[160:161], 1.0 op_sel_hi:[1,0]
	v_pk_add_f32 v[158:159], v[158:159], 1.0 op_sel_hi:[1,0]
	v_rcp_f32_e32 v160, v160
	v_rcp_f32_e32 v161, v161
	v_rcp_f32_e32 v158, v158
	v_rcp_f32_e32 v159, v159
	v_addc_co_u32_e32 v165, vcc, 0, v111, vcc
	v_pk_mul_f32 v[156:157], v[156:157], v[160:161]
	v_pk_mul_f32 v[138:139], v[138:139], v[158:159]
	v_pk_mul_f32 v[160:161], v[18:19], v[88:89]
	v_pk_mul_f32 v[170:171], v[30:31], v[96:97]
	v_pk_fma_f32 v[160:161], v[14:15], v[92:93], v[160:161]
	v_pk_fma_f32 v[170:171], v[26:27], v[102:103], v[170:171]
	v_pk_fma_f32 v[160:161], v[22:23], v[120:121], v[160:161]
	s_nop 0
	v_lshlrev_b32_e32 v43, 16, v130
	v_and_b32_e32 v130, 0xffff0000, v130
	v_lshlrev_b32_e32 v158, 16, v131
	v_and_b32_e32 v131, 0xffff0000, v131
	v_mul_f32_e32 v130, v157, v130
	v_mul_f32_e32 v131, v139, v131
	v_mul_f32_e32 v43, v156, v43
	v_mul_f32_e32 v138, v138, v158
	v_cvt_pk_bf16_f32 v130, v43, v130
	v_cvt_pk_bf16_f32 v131, v138, v131
	flat_store_dwordx2 v[162:163], v[130:131] offset:3584
	s_nop 1
	v_mov_b64_e32 v[138:139], v[186:187]
	v_pk_mul_f32 v[156:157], v[6:7], v[74:75]
	v_pk_mul_f32 v[158:159], v[4:5], v[70:71]
	v_pk_mul_f32 v[162:163], v[16:17], v[86:87]
	v_pk_fma_f32 v[158:159], v[0:1], v[82:83], v[158:159]
	v_pk_fma_f32 v[156:157], v[2:3], v[84:85], v[156:157]
	v_pk_fma_f32 v[162:163], v[12:13], v[90:91], v[162:163]
	v_pk_fma_f32 v[156:157], v[10:11], v[126:127], v[156:157]
	v_pk_fma_f32 v[158:159], v[8:9], v[122:123], v[158:159]
	v_lshlrev_b32_e32 v130, 16, v132
	v_and_b32_e32 v131, 0xffff0000, v132
	v_lshlrev_b32_e32 v132, 16, v133
	v_and_b32_e32 v133, 0xffff0000, v133
	v_pk_fma_f32 v[162:163], v[20:21], v[118:119], v[162:163]
	v_pk_add_f32 v[158:159], v[36:37], v[158:159]
	v_pk_add_f32 v[156:157], v[38:39], v[156:157]
	v_pk_fma_f32 v[170:171], v[34:35], v[132:133], v[170:171]
	v_pk_fma_f32 v[172:173], v[32:33], v[130:131], v[172:173]
	v_pk_add_f32 v[156:157], v[156:157], v[160:161]
	v_pk_add_f32 v[158:159], v[158:159], v[162:163]
	v_pk_add_f32 v[156:157], v[156:157], v[170:171]
	v_pk_add_f32 v[158:159], v[158:159], v[172:173]
	v_pk_mul_f32 v[160:161], v[156:157], v[156:157]
	v_pk_mul_f32 v[162:163], v[158:159], v[158:159]
	v_pk_fma_f32 v[160:161], v[160:161], s[26:27], v[154:155] op_sel_hi:[1,0,0] neg_lo:[1,0,0] neg_hi:[1,0,0]
	v_pk_fma_f32 v[162:163], v[162:163], s[26:27], v[154:155] op_sel_hi:[1,0,0] neg_lo:[1,0,0] neg_hi:[1,0,0]
	v_pk_mul_f32 v[160:161], v[156:157], v[160:161]
	v_pk_mul_f32 v[162:163], v[158:159], v[162:163]
	v_exp_f32_e32 v160, v160
	v_exp_f32_e32 v162, v162
	v_exp_f32_e32 v163, v163
	v_exp_f32_e32 v161, v161
	v_add_co_u32_e32 v170, vcc, s61, v100
	v_pk_add_f32 v[162:163], v[162:163], 1.0 op_sel_hi:[1,0]
	v_pk_add_f32 v[160:161], v[160:161], 1.0 op_sel_hi:[1,0]
	v_rcp_f32_e32 v162, v162
	v_rcp_f32_e32 v163, v163
	v_rcp_f32_e32 v160, v160
	v_rcp_f32_e32 v161, v161
	v_addc_co_u32_e32 v171, vcc, 0, v101, vcc
	v_pk_mul_f32 v[158:159], v[158:159], v[162:163]
	v_pk_mul_f32 v[156:157], v[156:157], v[160:161]
	v_pk_mul_f32 v[162:163], v[18:19], v[96:97]
	v_pk_mul_f32 v[172:173], v[30:31], v[108:109]
	v_pk_fma_f32 v[162:163], v[14:15], v[102:103], v[162:163]
	v_pk_fma_f32 v[172:173], v[26:27], v[114:115], v[172:173]
	v_pk_fma_f32 v[162:163], v[22:23], v[132:133], v[162:163]
	s_nop 0
	v_lshlrev_b32_e32 v43, 16, v138
	v_and_b32_e32 v138, 0xffff0000, v138
	v_lshlrev_b32_e32 v160, 16, v139
	v_and_b32_e32 v139, 0xffff0000, v139
	v_mul_f32_e32 v138, v159, v138
	v_mul_f32_e32 v139, v157, v139
	v_mul_f32_e32 v43, v158, v43
	v_mul_f32_e32 v156, v156, v160
	v_cvt_pk_bf16_f32 v138, v43, v138
	v_cvt_pk_bf16_f32 v139, v156, v139
	flat_store_dwordx2 v[164:165], v[138:139] offset:3584
	s_nop 1
	v_mov_b64_e32 v[156:157], v[188:189]
	v_pk_mul_f32 v[158:159], v[6:7], v[88:89]
	v_pk_mul_f32 v[160:161], v[4:5], v[86:87]
	v_pk_mul_f32 v[164:165], v[16:17], v[94:95]
	v_pk_fma_f32 v[160:161], v[0:1], v[90:91], v[160:161]
	v_pk_fma_f32 v[158:159], v[2:3], v[92:93], v[158:159]
	v_pk_fma_f32 v[164:165], v[12:13], v[98:99], v[164:165]
	v_pk_fma_f32 v[158:159], v[10:11], v[120:121], v[158:159]
	v_pk_fma_f32 v[160:161], v[8:9], v[118:119], v[160:161]
	v_lshlrev_b32_e32 v138, 16, v140
	v_and_b32_e32 v139, 0xffff0000, v140
	v_lshlrev_b32_e32 v140, 16, v141
	v_and_b32_e32 v141, 0xffff0000, v141
	v_pk_fma_f32 v[164:165], v[20:21], v[130:131], v[164:165]
	v_pk_add_f32 v[160:161], v[36:37], v[160:161]
	v_pk_add_f32 v[158:159], v[38:39], v[158:159]
	v_pk_fma_f32 v[172:173], v[34:35], v[140:141], v[172:173]
	v_pk_fma_f32 v[174:175], v[32:33], v[138:139], v[174:175]
	v_pk_add_f32 v[158:159], v[158:159], v[162:163]
	v_pk_add_f32 v[160:161], v[160:161], v[164:165]
	v_pk_add_f32 v[158:159], v[158:159], v[172:173]
	v_pk_add_f32 v[160:161], v[160:161], v[174:175]
	v_pk_mul_f32 v[162:163], v[158:159], v[158:159]
	v_pk_mul_f32 v[164:165], v[160:161], v[160:161]
	v_add_u32_e32 v43, 1, v168
	v_pk_fma_f32 v[164:165], v[164:165], s[26:27], v[154:155] op_sel_hi:[1,0,0] neg_lo:[1,0,0] neg_hi:[1,0,0]
	v_pk_fma_f32 v[154:155], v[162:163], s[26:27], v[154:155] op_sel_hi:[1,0,0] neg_lo:[1,0,0] neg_hi:[1,0,0]
	v_pk_mul_f32 v[162:163], v[160:161], v[164:165]
	v_pk_mul_f32 v[154:155], v[158:159], v[154:155]
	v_exp_f32_e32 v162, v162
	v_exp_f32_e32 v154, v154
	v_exp_f32_e32 v155, v155
	v_exp_f32_e32 v163, v163
	v_cmp_lt_u32_e32 vcc, v43, v53
	v_pk_add_f32 v[154:155], v[154:155], 1.0 op_sel_hi:[1,0]
	v_pk_add_f32 v[162:163], v[162:163], 1.0 op_sel_hi:[1,0]
	v_rcp_f32_e32 v154, v154
	v_rcp_f32_e32 v155, v155
	v_rcp_f32_e32 v162, v162
	v_rcp_f32_e32 v163, v163
	v_pk_mul_f32 v[154:155], v[158:159], v[154:155]
	v_pk_mul_f32 v[160:161], v[160:161], v[162:163]
	s_nop 0
	v_lshlrev_b32_e32 v159, 16, v157
	v_and_b32_e32 v157, 0xffff0000, v157
	v_lshlrev_b32_e32 v158, 16, v156
	v_and_b32_e32 v156, 0xffff0000, v156
	v_mul_f32_e32 v155, v155, v157
	v_mul_f32_e32 v158, v160, v158
	v_mul_f32_e32 v156, v161, v156
	v_mul_f32_e32 v159, v154, v159
	v_cvt_pk_bf16_f32 v154, v158, v156
	v_cvt_pk_bf16_f32 v155, v159, v155
	flat_store_dwordx2 v[170:171], v[154:155] offset:3584
	s_and_saveexec_b64 s[36:37], vcc
	s_cbranch_execz .LBB0_969
	v_cmp_gt_u32_e64 s[10:11], 61, v168
	v_mov_b32_e32 v154, v42
	v_mov_b32_e32 v155, v42
	s_and_b64 s[4:5], s[6:7], s[10:11]
	v_mov_b64_e32 v[158:159], v[154:155]
	s_and_saveexec_b64 s[46:47], s[4:5]
	s_cbranch_execz .LBB0_962
	v_add_u32_e32 v43, s34, v52
	v_add_u32_e32 v72, 0xfffac200, v43
	v_mov_b32_e32 v73, v42
	v_lshl_add_u64 v[72:73], v[44:45], 0, v[72:73]
	flat_load_dwordx2 v[158:159], v[72:73]

.LBB0_968:
	s_or_b64 exec, exec, s[10:11]
	v_add_co_u32_e32 v90, vcc, s62, v128
	v_pk_mul_f32 v[98:99], v[2:3], v[64:65]
	s_nop 0
	v_addc_co_u32_e32 v91, vcc, 0, v129, vcc
	flat_load_dwordx2 v[92:93], v[90:91] offset:1024
	v_lshl_add_u64 v[178:179], v[116:117], 0, s[90:91]
	v_lshl_add_u64 v[180:181], v[110:111], 0, s[90:91]
	v_lshl_add_u64 v[182:183], v[100:101], 0, s[90:91]
	global_load_dwordx2 v[184:185], v[178:179], off offset:-3072
	global_load_dwordx2 v[186:187], v[180:181], off offset:-3072
	global_load_dwordx2 v[188:189], v[182:183], off offset:-3072
	v_pk_mul_f32 v[102:103], v[0:1], v[62:63]
	v_lshlrev_b32_e32 v72, 16, v148
	v_and_b32_e32 v73, 0xffff0000, v148
	v_lshlrev_b32_e32 v76, 16, v149
	v_and_b32_e32 v77, 0xffff0000, v149
	v_pk_mul_f32 v[112:113], v[14:15], v[68:69]
	v_pk_mul_f32 v[114:115], v[12:13], v[66:67]
	v_pk_fma_f32 v[98:99], v[6:7], v[144:145], v[98:99]
	v_pk_fma_f32 v[102:103], v[4:5], v[142:143], v[102:103]
	v_lshlrev_b32_e32 v78, 16, v152
	v_and_b32_e32 v79, 0xffff0000, v152
	v_lshlrev_b32_e32 v80, 16, v153
	v_and_b32_e32 v81, 0xffff0000, v153
	v_pk_mul_f32 v[148:149], v[26:27], v[74:75]
	v_pk_mul_f32 v[152:153], v[24:25], v[70:71]
	v_pk_fma_f32 v[112:113], v[18:19], v[136:137], v[112:113]
	v_pk_fma_f32 v[114:115], v[16:17], v[134:135], v[114:115]
	v_pk_fma_f32 v[98:99], v[10:11], v[76:77], v[98:99]
	v_pk_fma_f32 v[102:103], v[8:9], v[72:73], v[102:103]
	v_lshlrev_b32_e32 v82, 16, v150
	v_and_b32_e32 v83, 0xffff0000, v150
	v_lshlrev_b32_e32 v84, 16, v151
	v_and_b32_e32 v85, 0xffff0000, v151
	v_pk_fma_f32 v[148:149], v[30:31], v[126:127], v[148:149]
	v_pk_fma_f32 v[152:153], v[28:29], v[122:123], v[152:153]
	v_pk_fma_f32 v[112:113], v[22:23], v[80:81], v[112:113]
	v_pk_fma_f32 v[114:115], v[20:21], v[78:79], v[114:115]
	v_pk_add_f32 v[98:99], v[38:39], v[98:99]
	v_pk_add_f32 v[102:103], v[36:37], v[102:103]
	v_pk_fma_f32 v[148:149], v[34:35], v[84:85], v[148:149]
	v_pk_fma_f32 v[152:153], v[32:33], v[82:83], v[152:153]
	v_pk_add_f32 v[98:99], v[98:99], v[112:113]
	v_pk_add_f32 v[102:103], v[102:103], v[114:115]
	v_pk_add_f32 v[98:99], v[98:99], v[148:149]
	v_pk_add_f32 v[102:103], v[102:103], v[152:153]
	v_mov_b64_e32 v[150:151], s[28:29]
	v_pk_mul_f32 v[112:113], v[98:99], v[98:99]
	v_pk_mul_f32 v[114:115], v[102:103], v[102:103]
	v_pk_fma_f32 v[112:113], v[112:113], s[26:27], v[150:151] op_sel_hi:[1,0,0] neg_lo:[1,0,0] neg_hi:[1,0,0]
	v_pk_fma_f32 v[114:115], v[114:115], s[26:27], v[150:151] op_sel_hi:[1,0,0] neg_lo:[1,0,0] neg_hi:[1,0,0]
	v_pk_mul_f32 v[112:113], v[98:99], v[112:113]
	v_pk_mul_f32 v[114:115], v[102:103], v[114:115]
	v_exp_f32_e32 v112, v112
	v_exp_f32_e32 v114, v114
	v_exp_f32_e32 v115, v115
	v_exp_f32_e32 v113, v113
	v_add_co_u32_e32 v148, vcc, s62, v116
	v_pk_add_f32 v[114:115], v[114:115], 1.0 op_sel_hi:[1,0]
	v_pk_add_f32 v[112:113], v[112:113], 1.0 op_sel_hi:[1,0]
	v_rcp_f32_e32 v114, v114
	v_rcp_f32_e32 v115, v115
	v_rcp_f32_e32 v112, v112
	v_rcp_f32_e32 v113, v113
	v_addc_co_u32_e32 v149, vcc, 0, v117, vcc
	v_pk_mul_f32 v[102:103], v[102:103], v[114:115]
	v_pk_mul_f32 v[98:99], v[98:99], v[112:113]
	v_pk_mul_f32 v[114:115], v[14:15], v[74:75]
	v_pk_mul_f32 v[152:153], v[26:27], v[88:89]
	v_pk_mul_f32 v[170:171], v[24:25], v[86:87]
	v_pk_fma_f32 v[114:115], v[18:19], v[126:127], v[114:115]
	v_pk_fma_f32 v[152:153], v[30:31], v[120:121], v[152:153]
	v_pk_fma_f32 v[170:171], v[28:29], v[118:119], v[170:171]
	v_pk_fma_f32 v[114:115], v[22:23], v[84:85], v[114:115]
	v_pk_mul_f32 v[172:173], v[24:25], v[94:95]
	v_pk_mul_f32 v[174:175], v[26:27], v[108:109]
	v_pk_fma_f32 v[172:173], v[28:29], v[130:131], v[172:173]
	v_pk_mul_f32 v[176:177], v[24:25], v[106:107]
	s_waitcnt vmcnt(0) lgkmcnt(0)
	v_lshlrev_b32_e32 v43, 16, v92
	v_and_b32_e32 v92, 0xffff0000, v92
	v_lshlrev_b32_e32 v112, 16, v93
	v_and_b32_e32 v93, 0xffff0000, v93
	v_mul_f32_e32 v92, v103, v92
	v_mul_f32_e32 v93, v99, v93
	v_mul_f32_e32 v43, v102, v43
	v_mul_f32_e32 v98, v98, v112
	v_cvt_pk_bf16_f32 v92, v43, v92
	v_cvt_pk_bf16_f32 v93, v98, v93
	flat_store_dwordx2 v[90:91], v[92:93] offset:1024
	s_nop 1
	v_mov_b64_e32 v[98:99], v[184:185]
	v_pk_mul_f32 v[102:103], v[2:3], v[68:69]
	v_pk_mul_f32 v[112:113], v[0:1], v[66:67]
	v_lshlrev_b32_e32 v90, 16, v146
	v_and_b32_e32 v91, 0xffff0000, v146
	v_lshlrev_b32_e32 v92, 16, v147
	v_and_b32_e32 v93, 0xffff0000, v147
	v_pk_mul_f32 v[146:147], v[12:13], v[70:71]
	v_pk_fma_f32 v[102:103], v[6:7], v[136:137], v[102:103]
	v_pk_fma_f32 v[112:113], v[4:5], v[134:135], v[112:113]
	v_pk_fma_f32 v[146:147], v[16:17], v[122:123], v[146:147]
	v_pk_fma_f32 v[102:103], v[10:11], v[80:81], v[102:103]
	v_pk_fma_f32 v[112:113], v[8:9], v[78:79], v[112:113]
	v_pk_fma_f32 v[146:147], v[20:21], v[82:83], v[146:147]
	v_pk_add_f32 v[102:103], v[38:39], v[102:103]
	v_pk_add_f32 v[112:113], v[36:37], v[112:113]
	v_pk_fma_f32 v[152:153], v[34:35], v[92:93], v[152:153]
	v_pk_fma_f32 v[170:171], v[32:33], v[90:91], v[170:171]
	v_pk_add_f32 v[102:103], v[102:103], v[114:115]
	v_pk_add_f32 v[112:113], v[112:113], v[146:147]
	v_pk_add_f32 v[102:103], v[102:103], v[152:153]
	v_pk_add_f32 v[112:113], v[112:113], v[170:171]
	v_pk_mul_f32 v[114:115], v[102:103], v[102:103]
	v_pk_mul_f32 v[146:147], v[112:113], v[112:113]
	v_pk_fma_f32 v[114:115], v[114:115], s[26:27], v[150:151] op_sel_hi:[1,0,0] neg_lo:[1,0,0] neg_hi:[1,0,0]
	v_pk_fma_f32 v[146:147], v[146:147], s[26:27], v[150:151] op_sel_hi:[1,0,0] neg_lo:[1,0,0] neg_hi:[1,0,0]
	v_pk_mul_f32 v[114:115], v[102:103], v[114:115]
	v_pk_mul_f32 v[146:147], v[112:113], v[146:147]
	v_exp_f32_e32 v114, v114
	v_exp_f32_e32 v146, v146
	v_exp_f32_e32 v147, v147
	v_exp_f32_e32 v115, v115
	v_add_co_u32_e32 v152, vcc, s62, v110
	v_pk_add_f32 v[146:147], v[146:147], 1.0 op_sel_hi:[1,0]
	v_pk_add_f32 v[114:115], v[114:115], 1.0 op_sel_hi:[1,0]
	v_rcp_f32_e32 v146, v146
	v_rcp_f32_e32 v147, v147
	v_rcp_f32_e32 v114, v114
	v_rcp_f32_e32 v115, v115
	v_addc_co_u32_e32 v153, vcc, 0, v111, vcc
	v_pk_mul_f32 v[112:113], v[112:113], v[146:147]
	v_pk_mul_f32 v[102:103], v[102:103], v[114:115]
	v_pk_mul_f32 v[146:147], v[14:15], v[88:89]
	v_pk_mul_f32 v[170:171], v[26:27], v[96:97]
	v_pk_fma_f32 v[146:147], v[18:19], v[120:121], v[146:147]
	v_pk_fma_f32 v[170:171], v[30:31], v[132:133], v[170:171]
	v_pk_fma_f32 v[146:147], v[22:23], v[92:93], v[146:147]
	s_nop 0
	v_lshlrev_b32_e32 v43, 16, v98
	v_and_b32_e32 v98, 0xffff0000, v98
	v_lshlrev_b32_e32 v114, 16, v99
	v_and_b32_e32 v99, 0xffff0000, v99
	v_mul_f32_e32 v98, v113, v98
	v_mul_f32_e32 v99, v103, v99
	v_mul_f32_e32 v43, v112, v43
	v_mul_f32_e32 v102, v102, v114
	v_cvt_pk_bf16_f32 v98, v43, v98
	v_cvt_pk_bf16_f32 v99, v102, v99
	flat_store_dwordx2 v[148:149], v[98:99] offset:1024
	s_nop 1
	v_mov_b64_e32 v[112:113], v[186:187]
	v_lshlrev_b32_e32 v98, 16, v124
	v_and_b32_e32 v99, 0xffff0000, v124
	v_lshlrev_b32_e32 v102, 16, v125
	v_and_b32_e32 v103, 0xffff0000, v125
	v_pk_mul_f32 v[114:115], v[2:3], v[74:75]
	v_pk_mul_f32 v[124:125], v[0:1], v[70:71]
	v_pk_mul_f32 v[148:149], v[12:13], v[86:87]
	v_pk_fma_f32 v[114:115], v[6:7], v[126:127], v[114:115]
	v_pk_fma_f32 v[124:125], v[4:5], v[122:123], v[124:125]
	v_pk_fma_f32 v[148:149], v[16:17], v[118:119], v[148:149]
	v_pk_fma_f32 v[114:115], v[10:11], v[84:85], v[114:115]
	v_pk_fma_f32 v[124:125], v[8:9], v[82:83], v[124:125]
	v_pk_fma_f32 v[148:149], v[20:21], v[90:91], v[148:149]
	v_pk_add_f32 v[114:115], v[38:39], v[114:115]
	v_pk_add_f32 v[124:125], v[36:37], v[124:125]
	v_pk_fma_f32 v[170:171], v[34:35], v[102:103], v[170:171]
	v_pk_fma_f32 v[172:173], v[32:33], v[98:99], v[172:173]
	v_pk_add_f32 v[114:115], v[114:115], v[146:147]
	v_pk_add_f32 v[124:125], v[124:125], v[148:149]
	v_pk_add_f32 v[114:115], v[114:115], v[170:171]
	v_pk_add_f32 v[124:125], v[124:125], v[172:173]
	v_pk_mul_f32 v[146:147], v[114:115], v[114:115]
	v_pk_mul_f32 v[148:149], v[124:125], v[124:125]
	v_pk_fma_f32 v[146:147], v[146:147], s[26:27], v[150:151] op_sel_hi:[1,0,0] neg_lo:[1,0,0] neg_hi:[1,0,0]
	v_pk_fma_f32 v[148:149], v[148:149], s[26:27], v[150:151] op_sel_hi:[1,0,0] neg_lo:[1,0,0] neg_hi:[1,0,0]
	v_pk_mul_f32 v[146:147], v[114:115], v[146:147]
	v_pk_mul_f32 v[148:149], v[124:125], v[148:149]
	v_exp_f32_e32 v146, v146
	v_exp_f32_e32 v148, v148
	v_exp_f32_e32 v149, v149
	v_exp_f32_e32 v147, v147
	v_add_co_u32_e32 v170, vcc, s62, v100
	v_pk_add_f32 v[148:149], v[148:149], 1.0 op_sel_hi:[1,0]
	v_pk_add_f32 v[146:147], v[146:147], 1.0 op_sel_hi:[1,0]
	v_rcp_f32_e32 v148, v148
	v_rcp_f32_e32 v149, v149
	v_rcp_f32_e32 v146, v146
	v_rcp_f32_e32 v147, v147
	v_addc_co_u32_e32 v171, vcc, 0, v101, vcc
	v_pk_mul_f32 v[124:125], v[124:125], v[148:149]
	v_pk_mul_f32 v[114:115], v[114:115], v[146:147]
	v_mov_b64_e32 v[148:149], v[158:159]
	v_pk_fma_f32 v[158:159], v[30:31], v[140:141], v[174:175]
	v_pk_fma_f32 v[174:175], v[28:29], v[138:139], v[176:177]
	s_nop 0
	v_lshlrev_b32_e32 v43, 16, v112
	v_and_b32_e32 v112, 0xffff0000, v112
	v_lshlrev_b32_e32 v146, 16, v113
	v_and_b32_e32 v113, 0xffff0000, v113
	v_mul_f32_e32 v112, v125, v112
	v_mul_f32_e32 v113, v115, v113
	v_mul_f32_e32 v43, v124, v43
	v_mul_f32_e32 v114, v114, v146
	v_cvt_pk_bf16_f32 v112, v43, v112
	v_cvt_pk_bf16_f32 v113, v114, v113
	flat_store_dwordx2 v[152:153], v[112:113] offset:1024
	s_nop 1
	v_mov_b64_e32 v[172:173], v[188:189]
	v_lshlrev_b32_e32 v112, 16, v104
	v_and_b32_e32 v113, 0xffff0000, v104
	v_lshlrev_b32_e32 v114, 16, v105
	v_and_b32_e32 v115, 0xffff0000, v105
	v_pk_mul_f32 v[104:105], v[2:3], v[88:89]
	v_pk_mul_f32 v[124:125], v[0:1], v[86:87]
	v_pk_mul_f32 v[146:147], v[14:15], v[96:97]
	v_pk_mul_f32 v[152:153], v[12:13], v[94:95]
	v_pk_fma_f32 v[104:105], v[6:7], v[120:121], v[104:105]
	v_pk_fma_f32 v[124:125], v[4:5], v[118:119], v[124:125]
	v_pk_fma_f32 v[146:147], v[18:19], v[132:133], v[146:147]
	v_pk_fma_f32 v[152:153], v[16:17], v[130:131], v[152:153]
	v_pk_fma_f32 v[104:105], v[10:11], v[92:93], v[104:105]
	v_pk_fma_f32 v[124:125], v[8:9], v[90:91], v[124:125]
	v_pk_fma_f32 v[146:147], v[22:23], v[102:103], v[146:147]
	v_pk_fma_f32 v[152:153], v[20:21], v[98:99], v[152:153]
	v_pk_add_f32 v[104:105], v[38:39], v[104:105]
	v_pk_add_f32 v[124:125], v[36:37], v[124:125]
	v_pk_fma_f32 v[158:159], v[34:35], v[114:115], v[158:159]
	v_pk_fma_f32 v[174:175], v[32:33], v[112:113], v[174:175]
	v_pk_add_f32 v[104:105], v[104:105], v[146:147]
	v_pk_add_f32 v[124:125], v[124:125], v[152:153]
	v_pk_add_f32 v[104:105], v[104:105], v[158:159]
	v_pk_add_f32 v[158:159], v[124:125], v[174:175]
	v_pk_mul_f32 v[124:125], v[104:105], v[104:105]
	v_pk_mul_f32 v[146:147], v[158:159], v[158:159]
	v_pk_fma_f32 v[124:125], v[124:125], s[26:27], v[150:151] op_sel_hi:[1,0,0] neg_lo:[1,0,0] neg_hi:[1,0,0]
	v_pk_fma_f32 v[146:147], v[146:147], s[26:27], v[150:151] op_sel_hi:[1,0,0] neg_lo:[1,0,0] neg_hi:[1,0,0]
	v_pk_mul_f32 v[124:125], v[104:105], v[124:125]
	v_pk_mul_f32 v[146:147], v[158:159], v[146:147]
	v_exp_f32_e32 v124, v124
	v_exp_f32_e32 v146, v146
	v_exp_f32_e32 v147, v147
	v_exp_f32_e32 v125, v125
	v_mov_b64_e32 v[152:153], v[154:155]
	v_mov_b64_e32 v[150:151], v[156:157]
	v_pk_add_f32 v[146:147], v[146:147], 1.0 op_sel_hi:[1,0]
	v_pk_add_f32 v[124:125], v[124:125], 1.0 op_sel_hi:[1,0]
	v_rcp_f32_e32 v154, v146
	v_rcp_f32_e32 v155, v147
	v_rcp_f32_e32 v156, v124
	v_rcp_f32_e32 v157, v125
	v_mov_b64_e32 v[146:147], v[160:161]
	v_pk_mul_f32 v[154:155], v[158:159], v[154:155]
	v_mov_b64_e32 v[124:125], v[162:163]
	v_pk_mul_f32 v[104:105], v[104:105], v[156:157]
	s_nop 0
	v_and_b32_e32 v158, 0xffff0000, v173
	v_lshlrev_b32_e32 v43, 16, v172
	v_and_b32_e32 v156, 0xffff0000, v172
	v_lshlrev_b32_e32 v157, 16, v173
	v_mul_f32_e32 v105, v105, v158
	v_mul_f32_e32 v43, v154, v43
	v_mul_f32_e32 v154, v155, v156
	v_mul_f32_e32 v155, v104, v157
	v_cvt_pk_bf16_f32 v104, v43, v154
	v_cvt_pk_bf16_f32 v105, v155, v105
	flat_store_dwordx2 v[170:171], v[104:105] offset:1024
	v_mov_b64_e32 v[104:105], v[164:165]
